# even attention: GLA sample chains pinned to designated workgroups on distinct CUs (blocks b<256 with (b>>3)&31 in {0,2,4,6}); rest of items from per-XCD queues
# speedup vs baseline: 1.0148x; 1.0148x over previous
.LBB0_1372:
	s_andn2_b64 vcc, exec, s[0:1]
	s_cbranch_vccnz .LBB0_1555
	s_getreg_b32 s80, hwreg(HW_REG_XCC_ID, 0, 4)
	s_and_b32 s0, s22, 16
	v_readlane_b32 s2, v252, 4
	v_readlane_b32 s3, v252, 5
	s_add_u32 s0, s0, 36
	s_lshl_b32 s0, s0, 2
	s_and_b32 s80, s80, 7
	s_mov_b32 s81, 0
	v_readlane_b32 s77, v254, 55
	s_nop 0
	s_bfe_u32 s9, s77, 0x50003
	s_and_b32 s8, s77, 7
	s_lshl_b32 s8, s8, 2
	s_lshr_b32 s10, s9, 1
	s_add_u32 s8, s8, s10
	s_and_b32 s10, s9, 0x19
	s_lshr_b32 s77, s77, 8
	s_or_b32 s10, s10, s77
	s_cmp_eq_u32 s10, 0
	s_cselect_b32 s77, s8, -1
	s_add_u32 s6, s2, s0
	s_addc_u32 s7, s3, 0
	v_mov_b32_e32 v0, v179
	s_waitcnt vmcnt(63) expcnt(7) lgkmcnt(15)
	s_barrier
	s_branch .LBB0_1376

.LBB0_1376:
	s_nop 0
	v_cmp_eq_u32_e32 vcc, 0, v0
	s_and_saveexec_b64 s[0:1], vcc
	s_cbranch_execz .LBB0_1380
	s_cmp_lt_i32 s77, 0
	s_cbranch_scc1 .Lxq_fetch
	s_mov_b32 s8, s77
	s_mov_b32 s77, -1
	s_branch .Lxq_put
.Lxq_fetch:
	s_lshl_b32 s8, s80, 2
	v_mov_b32_e32 v2, 1
	v_mov_b32_e32 v5, s8
	s_waitcnt vmcnt(0)
	global_atomic_add v2, v5, v2, s[6:7] sc0
	s_waitcnt vmcnt(0)
	v_readfirstlane_b32 s8, v2
	s_cmpk_lt_u32 s8, 0xe0
	s_cbranch_scc1 .Lxq_got
	s_add_u32 s81, s81, 1
	s_add_u32 s80, s80, 1
	s_and_b32 s80, s80, 7
	s_cmp_lt_u32 s81, 8
	s_cbranch_scc1 .Lxq_fetch
	s_mov_b32 s81, 8
	s_movk_i32 s8, 0x720
	s_branch .Lxq_put
.Lxq_got:
	s_add_u32 s8, s8, 4
